# prep S1 q-batch: the four l2norm butterfly chains (8 rows) issued together, 6 LDS round trips instead of 24
# baseline (speedup 1.0000x reference)
.LBB0_1702:
	s_waitcnt vmcnt(0)
	s_mov_b32 s14, 0x358637bd
	v_lshlrev_b32_e32 v226, 16, v32
	v_and_b32_e32 v227, 0xffff0000, v32
	v_lshlrev_b32_e32 v228, 16, v33
	v_and_b32_e32 v229, 0xffff0000, v33
	v_lshlrev_b32_e32 v230, 16, v41
	v_and_b32_e32 v231, 0xffff0000, v41
	v_lshlrev_b32_e32 v232, 16, v39
	v_and_b32_e32 v233, 0xffff0000, v39
	v_lshlrev_b32_e32 v234, 16, v37
	v_and_b32_e32 v235, 0xffff0000, v37
	v_lshlrev_b32_e32 v236, 16, v35
	v_and_b32_e32 v237, 0xffff0000, v35
	v_lshlrev_b32_e32 v238, 16, v31
	v_and_b32_e32 v239, 0xffff0000, v31
	v_lshlrev_b32_e32 v240, 16, v29
	v_and_b32_e32 v241, 0xffff0000, v29
	v_lshlrev_b32_e32 v242, 16, v27
	v_and_b32_e32 v243, 0xffff0000, v27
	v_lshlrev_b32_e32 v244, 16, v26
	v_and_b32_e32 v245, 0xffff0000, v26
	v_lshlrev_b32_e32 v54, 16, v44
	v_and_b32_e32 v55, 0xffff0000, v44
	v_pk_fma_f32 v[56:57], v[0:1], v[226:227], 0 op_sel_hi:[1,1,0]
	v_pk_fma_f32 v[58:59], v[0:1], v[228:229], 0 op_sel_hi:[1,1,0]
	v_pk_fma_f32 v[60:61], v[0:1], v[230:231], 0 op_sel_hi:[1,1,0]
	v_pk_fma_f32 v[62:63], v[0:1], v[232:233], 0 op_sel_hi:[1,1,0]
	v_pk_fma_f32 v[250:251], v[0:1], v[234:235], 0 op_sel_hi:[1,1,0]
	v_pk_fma_f32 v[252:253], v[0:1], v[236:237], 0 op_sel_hi:[1,1,0]
	v_pk_fma_f32 v[254:255], v[0:1], v[238:239], 0 op_sel_hi:[1,1,0]
	v_pk_fma_f32 v[48:49], v[0:1], v[240:241], 0 op_sel_hi:[1,1,0]
	v_pk_fma_f32 v[56:57], v[2:3], v[228:229], v[56:57]
	v_pk_fma_f32 v[58:59], v[2:3], v[230:231], v[58:59]
	v_pk_fma_f32 v[60:61], v[2:3], v[232:233], v[60:61]
	v_pk_fma_f32 v[62:63], v[2:3], v[234:235], v[62:63]
	v_pk_fma_f32 v[250:251], v[2:3], v[236:237], v[250:251]
	v_pk_fma_f32 v[252:253], v[2:3], v[238:239], v[252:253]
	v_pk_fma_f32 v[254:255], v[2:3], v[240:241], v[254:255]
	v_pk_fma_f32 v[48:49], v[2:3], v[242:243], v[48:49]
	v_pk_fma_f32 v[56:57], v[6:7], v[230:231], v[56:57]
	v_pk_fma_f32 v[58:59], v[6:7], v[232:233], v[58:59]
	v_pk_fma_f32 v[60:61], v[6:7], v[234:235], v[60:61]
	v_pk_fma_f32 v[62:63], v[6:7], v[236:237], v[62:63]
	v_pk_fma_f32 v[250:251], v[6:7], v[238:239], v[250:251]
	v_pk_fma_f32 v[252:253], v[6:7], v[240:241], v[252:253]
	v_pk_fma_f32 v[254:255], v[6:7], v[242:243], v[254:255]
	v_pk_fma_f32 v[48:49], v[6:7], v[244:245], v[48:49]
	v_pk_fma_f32 v[56:57], v[22:23], v[232:233], v[56:57]
	v_pk_fma_f32 v[58:59], v[22:23], v[234:235], v[58:59]
	v_pk_fma_f32 v[60:61], v[22:23], v[236:237], v[60:61]
	v_pk_fma_f32 v[62:63], v[22:23], v[238:239], v[62:63]
	v_pk_fma_f32 v[250:251], v[22:23], v[240:241], v[250:251]
	v_pk_fma_f32 v[252:253], v[22:23], v[242:243], v[252:253]
	v_pk_fma_f32 v[254:255], v[22:23], v[244:245], v[254:255]
	v_pk_fma_f32 v[48:49], v[22:23], v[54:55], v[48:49]
	v_mul_f32_e32 v227, 0xbfb8aa3b, v57
	v_mul_f32_e32 v226, 0xbfb8aa3b, v56
	v_mul_f32_e32 v229, 0xbfb8aa3b, v59
	v_mul_f32_e32 v228, 0xbfb8aa3b, v58
	v_mul_f32_e32 v231, 0xbfb8aa3b, v61
	v_mul_f32_e32 v230, 0xbfb8aa3b, v60
	v_mul_f32_e32 v233, 0xbfb8aa3b, v63
	v_mul_f32_e32 v232, 0xbfb8aa3b, v62
	v_mul_f32_e32 v235, 0xbfb8aa3b, v251
	v_mul_f32_e32 v234, 0xbfb8aa3b, v250
	v_mul_f32_e32 v237, 0xbfb8aa3b, v253
	v_mul_f32_e32 v236, 0xbfb8aa3b, v252
	v_mul_f32_e32 v239, 0xbfb8aa3b, v255
	v_mul_f32_e32 v238, 0xbfb8aa3b, v254
	v_mul_f32_e32 v241, 0xbfb8aa3b, v49
	v_mul_f32_e32 v240, 0xbfb8aa3b, v48
	v_exp_f32_e32 v227, v227
	v_exp_f32_e32 v226, v226
	v_exp_f32_e32 v229, v229
	v_exp_f32_e32 v228, v228
	v_exp_f32_e32 v231, v231
	v_exp_f32_e32 v230, v230
	v_exp_f32_e32 v233, v233
	v_exp_f32_e32 v232, v232
	v_exp_f32_e32 v235, v235
	v_exp_f32_e32 v234, v234
	v_exp_f32_e32 v237, v237
	v_exp_f32_e32 v236, v236
	v_exp_f32_e32 v239, v239
	v_exp_f32_e32 v238, v238
	v_exp_f32_e32 v241, v241
	v_exp_f32_e32 v240, v240
	v_add_f32_e32 v227, 1.0, v227
	v_add_f32_e32 v226, 1.0, v226
	v_add_f32_e32 v229, 1.0, v229
	v_add_f32_e32 v228, 1.0, v228
	v_add_f32_e32 v231, 1.0, v231
	v_add_f32_e32 v230, 1.0, v230
	v_add_f32_e32 v233, 1.0, v233
	v_add_f32_e32 v232, 1.0, v232
	v_add_f32_e32 v235, 1.0, v235
	v_add_f32_e32 v234, 1.0, v234
	v_add_f32_e32 v237, 1.0, v237
	v_add_f32_e32 v236, 1.0, v236
	v_add_f32_e32 v239, 1.0, v239
	v_add_f32_e32 v238, 1.0, v238
	v_add_f32_e32 v241, 1.0, v241
	v_add_f32_e32 v240, 1.0, v240
	v_rcp_f32_e32 v227, v227
	v_rcp_f32_e32 v226, v226
	v_rcp_f32_e32 v229, v229
	v_rcp_f32_e32 v228, v228
	v_rcp_f32_e32 v231, v231
	v_rcp_f32_e32 v230, v230
	v_rcp_f32_e32 v233, v233
	v_rcp_f32_e32 v232, v232
	v_rcp_f32_e32 v235, v235
	v_rcp_f32_e32 v234, v234
	v_rcp_f32_e32 v237, v237
	v_rcp_f32_e32 v236, v236
	v_rcp_f32_e32 v239, v239
	v_rcp_f32_e32 v238, v238
	v_rcp_f32_e32 v241, v241
	v_rcp_f32_e32 v240, v240
	v_pk_mul_f32 v[56:57], v[56:57], v[226:227]
	v_pk_mul_f32 v[58:59], v[58:59], v[228:229]
	v_pk_mul_f32 v[60:61], v[60:61], v[230:231]
	v_pk_mul_f32 v[62:63], v[62:63], v[232:233]
	v_pk_mul_f32 v[250:251], v[250:251], v[234:235]
	v_pk_mul_f32 v[252:253], v[252:253], v[236:237]
	v_pk_mul_f32 v[254:255], v[254:255], v[238:239]
	v_pk_mul_f32 v[48:49], v[48:49], v[240:241]
	v_pk_mul_f32 v[226:227], v[56:57], v[56:57]
	v_pk_mul_f32 v[228:229], v[58:59], v[58:59]
	v_pk_mul_f32 v[230:231], v[60:61], v[60:61]
	v_pk_mul_f32 v[232:233], v[62:63], v[62:63]
	v_pk_mul_f32 v[234:235], v[250:251], v[250:251]
	v_pk_mul_f32 v[236:237], v[252:253], v[252:253]
	v_pk_mul_f32 v[238:239], v[254:255], v[254:255]
	v_pk_mul_f32 v[240:241], v[48:49], v[48:49]
	v_add_f32_e32 v24, v227, v226
	v_add_f32_e32 v25, v229, v228
	v_add_f32_e32 v26, v231, v230
	v_add_f32_e32 v27, v233, v232
	v_add_f32_e32 v28, v235, v234
	v_add_f32_e32 v29, v237, v236
	v_add_f32_e32 v30, v239, v238
	v_add_f32_e32 v31, v241, v240
	ds_bpermute_b32 v32, v159, v24
	ds_bpermute_b32 v33, v159, v25
	ds_bpermute_b32 v34, v159, v26
	ds_bpermute_b32 v35, v159, v27
	ds_bpermute_b32 v36, v159, v28
	ds_bpermute_b32 v37, v159, v29
	ds_bpermute_b32 v38, v159, v30
	ds_bpermute_b32 v39, v159, v31
	s_waitcnt lgkmcnt(0)
	v_pk_add_f32 v[24:25], v[24:25], v[32:33]
	v_pk_add_f32 v[26:27], v[26:27], v[34:35]
	v_pk_add_f32 v[28:29], v[28:29], v[36:37]
	v_pk_add_f32 v[30:31], v[30:31], v[38:39]
	ds_bpermute_b32 v32, v166, v24
	ds_bpermute_b32 v33, v166, v25
	ds_bpermute_b32 v34, v166, v26
	ds_bpermute_b32 v35, v166, v27
	ds_bpermute_b32 v36, v166, v28
	ds_bpermute_b32 v37, v166, v29
	ds_bpermute_b32 v38, v166, v30
	ds_bpermute_b32 v39, v166, v31
	s_waitcnt lgkmcnt(0)
	v_pk_add_f32 v[24:25], v[24:25], v[32:33]
	v_pk_add_f32 v[26:27], v[26:27], v[34:35]
	v_pk_add_f32 v[28:29], v[28:29], v[36:37]
	v_pk_add_f32 v[30:31], v[30:31], v[38:39]
	ds_bpermute_b32 v32, v167, v24
	ds_bpermute_b32 v33, v167, v25
	ds_bpermute_b32 v34, v167, v26
	ds_bpermute_b32 v35, v167, v27
	ds_bpermute_b32 v36, v167, v28
	ds_bpermute_b32 v37, v167, v29
	ds_bpermute_b32 v38, v167, v30
	ds_bpermute_b32 v39, v167, v31
	s_waitcnt lgkmcnt(0)
	v_pk_add_f32 v[24:25], v[24:25], v[32:33]
	v_pk_add_f32 v[26:27], v[26:27], v[34:35]
	v_pk_add_f32 v[28:29], v[28:29], v[36:37]
	v_pk_add_f32 v[30:31], v[30:31], v[38:39]
	ds_bpermute_b32 v32, v168, v24
	ds_bpermute_b32 v33, v168, v25
	ds_bpermute_b32 v34, v168, v26
	ds_bpermute_b32 v35, v168, v27
	ds_bpermute_b32 v36, v168, v28
	ds_bpermute_b32 v37, v168, v29
	ds_bpermute_b32 v38, v168, v30
	ds_bpermute_b32 v39, v168, v31
	s_waitcnt lgkmcnt(0)
	v_pk_add_f32 v[24:25], v[24:25], v[32:33]
	v_pk_add_f32 v[26:27], v[26:27], v[34:35]
	v_pk_add_f32 v[28:29], v[28:29], v[36:37]
	v_pk_add_f32 v[30:31], v[30:31], v[38:39]
	ds_bpermute_b32 v32, v169, v24
	ds_bpermute_b32 v33, v169, v25
	ds_bpermute_b32 v34, v169, v26
	ds_bpermute_b32 v35, v169, v27
	ds_bpermute_b32 v36, v169, v28
	ds_bpermute_b32 v37, v169, v29
	ds_bpermute_b32 v38, v169, v30
	ds_bpermute_b32 v39, v169, v31
	s_waitcnt lgkmcnt(0)
	v_pk_add_f32 v[24:25], v[24:25], v[32:33]
	v_pk_add_f32 v[26:27], v[26:27], v[34:35]
	v_pk_add_f32 v[28:29], v[28:29], v[36:37]
	v_pk_add_f32 v[30:31], v[30:31], v[38:39]
	ds_bpermute_b32 v32, v170, v24
	ds_bpermute_b32 v33, v170, v25
	ds_bpermute_b32 v34, v170, v26
	ds_bpermute_b32 v35, v170, v27
	ds_bpermute_b32 v36, v170, v28
	ds_bpermute_b32 v37, v170, v29
	ds_bpermute_b32 v38, v170, v30
	ds_bpermute_b32 v39, v170, v31
	s_waitcnt lgkmcnt(0)
	v_pk_add_f32 v[24:25], v[24:25], v[32:33]
	v_pk_add_f32 v[26:27], v[26:27], v[34:35]
	v_pk_add_f32 v[28:29], v[28:29], v[36:37]
	v_pk_add_f32 v[30:31], v[30:31], v[38:39]
	s_nop 0
	v_add_f32_e32 v24, s14, v24
	v_add_f32_e32 v25, s14, v25
	v_add_f32_e32 v26, s14, v26
	v_add_f32_e32 v27, s14, v27
	v_add_f32_e32 v28, s14, v28
	v_add_f32_e32 v29, s14, v29
	v_add_f32_e32 v30, s14, v30
	v_add_f32_e32 v31, s14, v31
	v_mul_f32_e32 v46, 0x4b800000, v24
	v_mul_f32_e32 v47, 0x4b800000, v25
	v_cmp_gt_f32_e32 vcc, s26, v24
	v_cmp_gt_f32_e64 s[4:5], s26, v25
	s_nop 0
	v_cndmask_b32_e32 v24, v24, v46, vcc
	v_cndmask_b32_e64 v25, v25, v47, s[4:5]
	v_rsq_f32_e32 v24, v24
	v_rsq_f32_e32 v25, v25
	v_mul_f32_e32 v46, 0x45800000, v24
	v_mul_f32_e32 v47, 0x45800000, v25
	v_cndmask_b32_e32 v24, v24, v46, vcc
	v_cndmask_b32_e64 v25, v25, v47, s[4:5]
	v_mul_f32_e32 v50, 0x4b800000, v26
	v_mul_f32_e32 v51, 0x4b800000, v27
	v_cmp_gt_f32_e32 vcc, s26, v26
	v_cmp_gt_f32_e64 s[4:5], s26, v27
	s_nop 0
	v_cndmask_b32_e32 v26, v26, v50, vcc
	v_cndmask_b32_e64 v27, v27, v51, s[4:5]
	v_rsq_f32_e32 v26, v26
	v_rsq_f32_e32 v27, v27
	v_mul_f32_e32 v50, 0x45800000, v26
	v_mul_f32_e32 v51, 0x45800000, v27
	v_cndmask_b32_e32 v26, v26, v50, vcc
	v_cndmask_b32_e64 v27, v27, v51, s[4:5]
	v_mul_f32_e32 v52, 0x4b800000, v28
	v_mul_f32_e32 v53, 0x4b800000, v29
	v_cmp_gt_f32_e32 vcc, s26, v28
	v_cmp_gt_f32_e64 s[4:5], s26, v29
	s_nop 0
	v_cndmask_b32_e32 v28, v28, v52, vcc
	v_cndmask_b32_e64 v29, v29, v53, s[4:5]
	v_rsq_f32_e32 v28, v28
	v_rsq_f32_e32 v29, v29
	v_mul_f32_e32 v52, 0x45800000, v28
	v_mul_f32_e32 v53, 0x45800000, v29
	v_cndmask_b32_e32 v28, v28, v52, vcc
	v_cndmask_b32_e64 v29, v29, v53, s[4:5]
	v_mul_f32_e32 v40, 0x4b800000, v30
	v_mul_f32_e32 v45, 0x4b800000, v31
	v_cmp_gt_f32_e32 vcc, s26, v30
	v_cmp_gt_f32_e64 s[4:5], s26, v31
	s_nop 0
	v_cndmask_b32_e32 v30, v30, v40, vcc
	v_cndmask_b32_e64 v31, v31, v45, s[4:5]
	v_rsq_f32_e32 v30, v30
	v_rsq_f32_e32 v31, v31
	v_mul_f32_e32 v40, 0x45800000, v30
	v_mul_f32_e32 v45, 0x45800000, v31
	v_cndmask_b32_e32 v30, v30, v40, vcc
	v_cndmask_b32_e64 v31, v31, v45, s[4:5]
	v_mul_f32_e32 v226, 0x3db504f3, v24
	v_mul_f32_e32 v228, 0x3db504f3, v25
	v_mul_f32_e32 v230, 0x3db504f3, v26
	v_mul_f32_e32 v232, 0x3db504f3, v27
	v_mul_f32_e32 v234, 0x3db504f3, v28
	v_mul_f32_e32 v236, 0x3db504f3, v29
	v_mul_f32_e32 v238, 0x3db504f3, v30
	v_mul_f32_e32 v240, 0x3db504f3, v31
	v_pk_mul_f32 v[56:57], v[56:57], v[226:227] op_sel_hi:[1,0]
	v_pk_mul_f32 v[58:59], v[58:59], v[228:229] op_sel_hi:[1,0]
	v_pk_mul_f32 v[60:61], v[60:61], v[230:231] op_sel_hi:[1,0]
	v_pk_mul_f32 v[62:63], v[62:63], v[232:233] op_sel_hi:[1,0]
	v_pk_mul_f32 v[250:251], v[250:251], v[234:235] op_sel_hi:[1,0]
	v_pk_mul_f32 v[252:253], v[252:253], v[236:237] op_sel_hi:[1,0]
	v_pk_mul_f32 v[254:255], v[254:255], v[238:239] op_sel_hi:[1,0]
	v_pk_mul_f32 v[48:49], v[48:49], v[240:241] op_sel_hi:[1,0]
	v_cvt_pk_bf16_f32 v46, v56, v57
	v_cvt_pk_bf16_f32 v47, v58, v59
	v_cvt_pk_bf16_f32 v50, v60, v61
	v_cvt_pk_bf16_f32 v51, v62, v63
	v_cvt_pk_bf16_f32 v52, v250, v251
	v_cvt_pk_bf16_f32 v53, v252, v253
	v_cvt_pk_bf16_f32 v40, v254, v255
	v_cvt_pk_bf16_f32 v45, v48, v49
	ds_write_b32 v204, v46 offset:32768
	ds_write_b32 v205, v47 offset:32768
	ds_write_b32 v206, v50 offset:32768
	ds_write_b32 v207, v51 offset:32768
	ds_write_b32 v222, v52 offset:32768
	ds_write_b32 v223, v53 offset:32768
	ds_write_b32 v224, v40 offset:32768
	ds_write_b32 v225, v45 offset:32768
	v_add_u32_e32 v0, 0x300, v4
	v_ashrrev_i32_e32 v1, 31, v0
	v_lshl_add_u64 v[24:25], v[0:1], 2, v[8:9]
	v_add_co_u32_e32 v6, vcc, 0x2000, v24
	global_load_dwordx2 v[2:3], v[24:25], off
	s_nop 0
	v_addc_co_u32_e32 v7, vcc, 0, v25, vcc
	v_add_co_u32_e32 v22, vcc, 0x4000, v24
	global_load_dwordx2 v[6:7], v[6:7], off offset:1024
	s_nop 0
	v_addc_co_u32_e32 v23, vcc, 0, v25, vcc
	global_load_dwordx2 v[22:23], v[22:23], off offset:2048
	v_add_co_u32_e32 v24, vcc, 0x6000, v24
	v_lshl_add_u64 v[0:1], v[0:1], 1, s[16:17]
	s_nop 0
	v_addc_co_u32_e32 v25, vcc, 0, v25, vcc
	global_load_dwordx2 v[24:25], v[24:25], off offset:3072
	s_and_b64 vcc, exec, s[80:81]
	s_cbranch_vccnz .LBB0_1704
	v_mad_u64_u32 v[26:27], s[4:5], s29, v221, v[0:1]
	global_load_dword v5, v[26:27], off
